# loop-edge edit: differential-attention KV loop back edge rotated (conditional branch is the back edge, kt update above the barrier)
# baseline (speedup 1.0000x reference)
; #define LAS __attribute__((address_space(3)))
; __device__ __forceinline__ void diff_attn_item(CParams& p, int j, int layer, LAS unsigned char* lds, int b, int h, int qb, int tid_in, int lane_in, int wave) {
;     ...
;     for (int kt = 0; kt < nkt; ++kt) {
;         const int k0 = kt * 64; const int cur = kt & 1;
;         const LAS h16* Ks = Ks0 + cur * 8704; const LAS h16* Vt = Vt0 + cur * 9216;
;         if (kt + 1 < nkt) ATT_STAGE(cur ^ 1, 512 + h * 128, 1024 + h * 128, kt + 2);
;     ...
;         __syncthreads();
;     }
.LdiffA_end:
.LBB0_670:
	s_or_b64 exec, exec, s[4:5]
	s_add_i32 s12, s38, 1
	s_add_i32 s40, s40, 64
	s_cmp_eq_u32 s38, s37
	s_mov_b32 s38, s12
	v_subrev_u32_e32 v212, 64, v212
	s_waitcnt lgkmcnt(0)
	s_barrier
	s_cbranch_scc0 .LBB0_598
